# hot loop headers (in-proj, out-proj, both fox tile loops) aligned to 64 bytes
# speedup vs baseline: 1.0088x; 1.0088x over previous
; #define WAIT_V(n) asm volatile("s_waitcnt vmcnt(" #n ")" ::: "memory")
; #define BAR __builtin_amdgcn_s_barrier()
; #define LDA_(dst, ai) _Pragma("unroll") for (int m = 0; m < 4; ++m) dst[m] = *(const bf16x8*)(sb + (ai) * 8192 + la0 + m * 1024)
; #define LDB_(dst) _Pragma("unroll") for (int bj = 0; bj < 2; ++bj) _Pragma("unroll") for (int n = 0; n < 2; ++n) dst[bj][n] = *(const bf16x8*)(sb + 16384 + bj * 8192 + lb0 + n * 1024)
; template <int MODE>
; DI void gemm_phase(const Params& p, int layer, int hf, unsigned char* shmc, int tid) {
;     ...
;     for (int kt = 0; kt < nt; ++kt) {
;       const int rem = nt - 1 - kt;
;       if (rem >= 2) WAIT_V(8); else if (rem == 1) WAIT_V(4); else WAIT_V(0);
;       BAR;
;       const unsigned char* sb = shmc + (kt & 3) * 32768;
;     ...
;       {
;         bf16x8 b0[2][2], a0[4], a1[4];
;         LDB_(b0); LDA_(a0, 0);
.Lg0_wdone:
	s_barrier
	ds_read_b128 v[140:143], v194 offset:16384
	ds_read_b128 v[144:147], v194 offset:17408
	ds_read_b128 v[136:139], v194 offset:24576
	ds_read_b128 v[128:131], v194 offset:25600
	ds_read_b128 v[132:135], v191
	ds_read_b128 v[148:151], v191 offset:1024
	ds_read_b128 v[152:155], v191 offset:2048
	ds_read_b128 v[204:207], v191 offset:3072
	.p2align 6

; DI void fox_unit(const Params& p, int hf, int bl, int fh, int qb, unsigned char* shm, int tid, bool dry = false) {
;     ...
;   f32x4 o[2][4];
; #pragma unroll
;   for (int mi = 0; mi < 2; ++mi)
; #pragma unroll
;     for (int d = 0; d < 4; ++d) o[mi][d] = (f32x4){0.f, 0.f, 0.f, 0.f};
;   float mrun[2] = {-1e30f, -1e30f}, lsum[2] = {0.f, 0.f};
;   const int skey = tid >> 3, sdg = tid & 7;
;   const int kst = ((skey >> 4) * 2 + (sdg >> 2)) * 1024 + ((((skey & 15) * 64) + (sdg & 3) * 16) ^ (((skey >> 3) & 1) << 5));
;   uint4 kreg, vreg; float freg = 0.f;
;   {
;     const size_t r = (size_t)(kt0 * 64 + skey) * NP;
;     kreg = *(const uint4*)(projb + r + C_FK + fh * 64 + sdg * 8); vreg = *(const uint4*)(projb + r + C_FV + fh * 64 + sdg * 8);
;     if (tid < 64) freg = (Fref - F[kt0 * 64 + tid]) * LOG2E;
;   }
;   {
;     bf16_t* sK = (bf16_t*)(shm + (kt0 & 1) * STG); bf16_t* sV = sK + 64 * 72; float* sFk = (float*)(sV + 64 * 72);
;     *(uint4*)((unsigned char*)sK + kst) = kreg; *(uint4*)(sV + skey * 72 + sdg * 8) = vreg;
;     if (tid < 64) sFk[tid] = freg;
;   }
;   __syncthreads();
;   for (int kt = kt0; kt < nkt; ++kt) {
.LBB0_481:
	v_mov_b32_e32 v129, 0
	s_andn2_b64 vcc, exec, s[4:5]
	v_mov_b32_e32 v128, v129
	v_mov_b32_e32 v143, v129
	v_mov_b32_e32 v142, v129
	v_mov_b32_e32 v145, v129
	v_mov_b32_e32 v144, v129
	v_mov_b32_e32 v139, v129
	v_mov_b32_e32 v138, v129
	v_mov_b32_e32 v141, v129
	v_mov_b32_e32 v140, v129
	v_mov_b32_e32 v135, v129
	v_mov_b32_e32 v134, v129
	v_mov_b32_e32 v137, v129
	v_mov_b32_e32 v136, v129
	v_mov_b32_e32 v131, v129
	v_mov_b32_e32 v130, v129
	v_mov_b32_e32 v133, v129
	v_mov_b32_e32 v132, v129
	v_mov_b32_e32 v123, v129
	v_mov_b32_e32 v122, v129
	v_mov_b32_e32 v125, v129
	v_mov_b32_e32 v124, v129
	v_mov_b32_e32 v119, v129
	v_mov_b32_e32 v118, v129
	v_mov_b32_e32 v121, v129
	v_mov_b32_e32 v120, v129
	v_mov_b32_e32 v115, v129
	v_mov_b32_e32 v114, v129
	v_mov_b32_e32 v117, v129
	v_mov_b32_e32 v116, v129
	v_mov_b32_e32 v111, v129
	v_mov_b32_e32 v110, v129
	v_mov_b32_e32 v113, v129
	v_mov_b32_e32 v112, v129
	s_cbranch_vccnz .LBB0_635
	v_or_b32_e32 v212, 31, v28
	v_lshlrev_b32_e32 v28, 2, v27
	v_lshlrev_b32_e32 v26, 6, v27
	v_and_b32_e32 v29, 32, v28
	v_bitop3_b32 v213, v26, v29, v24 bitop3:0x36
	v_lshrrev_b32_e32 v24, 2, v27
	v_or_b32_e32 v24, v209, v24
	v_mov_b32_e32 v112, 0
	v_and_b32_e32 v214, 12, v28
	v_mul_u32_u24_e32 v215, 0x90, v24
	v_add_u32_e32 v216, 64, v205
	v_add_u32_e32 v217, 64, v25
	v_readfirstlane_b32 s99, v205
	s_nop 3
	s_lshr_b32 s99, s99, 8
	v_mov_b32_e32 v219, 0xf149f2ca
	v_mov_b32_e32 v113, v112
	v_mov_b32_e32 v110, v112
	v_mov_b32_e32 v111, v112
	v_mov_b32_e32 v116, v112
	v_mov_b32_e32 v117, v112
	v_mov_b32_e32 v114, v112
	v_mov_b32_e32 v115, v112
	v_mov_b32_e32 v120, v112
	v_mov_b32_e32 v121, v112
	v_mov_b32_e32 v118, v112
	v_mov_b32_e32 v119, v112
	v_mov_b32_e32 v124, v112
	v_mov_b32_e32 v125, v112
	v_mov_b32_e32 v122, v112
	v_mov_b32_e32 v123, v112
	v_mov_b32_e32 v132, v112
	v_mov_b32_e32 v133, v112
	v_mov_b32_e32 v130, v112
	v_mov_b32_e32 v131, v112
	v_mov_b32_e32 v136, v112
	v_mov_b32_e32 v137, v112
	v_mov_b32_e32 v134, v112
	v_mov_b32_e32 v135, v112
	v_mov_b32_e32 v140, v112
	v_mov_b32_e32 v141, v112
	v_mov_b32_e32 v138, v112
	v_mov_b32_e32 v139, v112
	v_mov_b32_e32 v144, v112
	v_mov_b32_e32 v145, v112
	v_mov_b32_e32 v142, v112
	v_mov_b32_e32 v143, v112
	v_mov_b32_e32 v128, v112
	v_mov_b32_e32 v129, v112
	v_mov_b32_e32 v218, 0xf149f2ca
	s_mov_b32 s98, 0
	v_mov_b32_e32 v224, 0x7149f2ca
	v_mov_b32_e32 v225, v224
	v_mov_b32_e32 v226, v224
	v_mov_b32_e32 v227, v224
	v_mov_b32_e32 v228, v224
	v_mov_b32_e32 v229, v224
	v_mov_b32_e32 v230, v224
	v_mov_b32_e32 v231, v224
	.p2align 6

; template <int MODE>
; DI void gemm_phase(const Params& p, int layer, int hf, unsigned char* shmc, int tid) {
;     ...
;     const bf16_t* gA = (MODE == 0) ? A + (size_t)(brow >> 7) * nt * 4096 : A + (size_t)brow * lda; const bf16_t* gB = Bt + (size_t)(bcol >> 7) * nt * 4096;
;     ...
;     if (!pre) { STAGE_ALL(0, 0); STAGE_ALL(1, 1); }
;     STAGE_ALL(2, 2);
.LBB0_692:
	v_mov_b32_e32 v2, v169
	s_lshl_b32 s15, s6, 8
	s_mul_i32 s4, s6, 0x340000
	s_mul_hi_i32 s5, s15, 0x3400
	v_lshlrev_b32_e32 v0, 4, v2
	v_and_b32_e32 v1, 32, v2
	s_add_u32 s4, s35, s4
	v_readlane_b32 s6, v253, 40
	v_add_u32_e32 v4, 32, v0
	v_bfe_u32 v3, v2, 2, 23
	v_bitop3_b32 v0, v0, v1, 48 bitop3:0x6c
	s_addc_u32 s5, s6, s5
	s_lshl_b32 s6, s14, 1
	v_lshrrev_b32_e32 v0, 1, v0
	v_mul_u32_u24_e32 v1, 0x1a00, v3
	s_ashr_i32 s7, s6, 31
	v_or_b32_e32 v0, v1, v0
	s_lshl_b64 s[6:7], s[6:7], 19
	v_readlane_b32 s8, v254, 41
	v_ashrrev_i32_e32 v1, 31, v0
	v_add_u32_e32 v5, 0x4000, v4
	v_readfirstlane_b32 s10, v4
	s_add_u32 s8, s8, s6
	v_readlane_b32 s9, v254, 42
	v_lshl_add_u64 v[0:1], v[0:1], 1, s[4:5]
	v_lshlrev_b32_e32 v2, 3, v2
	s_mov_b32 m0, s10
	v_readfirstlane_b32 s10, v5
	s_addc_u32 s9, s9, s7
	v_ashrrev_i32_e32 v3, 31, v2
	global_load_lds_dwordx4 v[0:1], off
	s_mov_b32 m0, s10
	s_mov_b64 s[10:11], 0x1a0000
	v_add_u32_e32 v5, 0x2000, v4
	v_lshl_add_u64 v[2:3], v[2:3], 1, s[8:9]
	v_lshl_add_u64 v[0:1], v[0:1], 0, s[10:11]
	v_readfirstlane_b32 s10, v5
	global_load_lds_dwordx4 v[2:3], off
	s_mov_b32 m0, s10
	s_mov_b64 s[10:11], 0x80000
	global_load_lds_dwordx4 v[0:1], off
	v_lshl_add_u64 v[0:1], v[2:3], 0, s[10:11]
	v_add_u32_e32 v2, 0x6000, v4
	s_mov_b32 s16, 0
	v_readfirstlane_b32 s10, v2
	s_mov_b32 m0, s10
	v_mov_b32_e32 v2, v169
	global_load_lds_dwordx4 v[0:1], off
	s_movk_i32 s17, 0x60
	v_lshlrev_b32_e32 v0, 4, v2
	v_and_b32_e32 v1, 32, v2
	v_add_u32_e32 v6, 32, v0
	v_bfe_u32 v3, v2, 2, 23
	v_bitop3_b32 v0, v0, v1, 48 bitop3:0x6c
	v_lshrrev_b32_e32 v0, 1, v0
	v_mul_u32_u24_e32 v1, 0x1a00, v3
	v_or_b32_e32 v0, v1, v0
	v_add_u32_e32 v7, 0x8000, v6
	v_ashrrev_i32_e32 v1, 31, v0
	v_lshlrev_b32_e32 v2, 3, v2
	v_lshl_add_u64 v[0:1], v[0:1], 1, s[4:5]
	v_ashrrev_i32_e32 v3, 31, v2
	v_readfirstlane_b32 s10, v7
	v_add_u32_e32 v8, 0xc000, v6
	v_lshl_add_u64 v[4:5], v[0:1], 0, 64
	s_mov_b32 m0, s10
	v_lshl_add_u64 v[2:3], v[2:3], 1, s[8:9]
	s_mov_b64 s[10:11], 0x2000
	global_load_lds_dwordx4 v[4:5], off
	v_lshl_add_u64 v[4:5], v[2:3], 0, s[10:11]
	v_readfirstlane_b32 s10, v8
	s_mov_b32 m0, s10
	s_mov_b64 s[10:11], 0x1a0040
	global_load_lds_dwordx4 v[4:5], off
	v_add_u32_e32 v4, 0xa000, v6
	v_lshl_add_u64 v[0:1], v[0:1], 0, s[10:11]
	v_readfirstlane_b32 s10, v4
	s_mov_b32 m0, s10
	s_mov_b64 s[10:11], 0x82000
	global_load_lds_dwordx4 v[0:1], off
	v_lshl_add_u64 v[0:1], v[2:3], 0, s[10:11]
	v_add_u32_e32 v2, 0xe000, v6
	s_mov_b32 s18, 0x18000
	v_readfirstlane_b32 s10, v2
	s_mov_b32 m0, s10
	v_mov_b32_e32 v2, v169
	global_load_lds_dwordx4 v[0:1], off
	v_readlane_b32 s10, v253, 62
	v_lshlrev_b32_e32 v0, 4, v2
	v_and_b32_e32 v1, 32, v2
	v_add_u32_e32 v6, s10, v0
	v_bfe_u32 v3, v2, 2, 23
	v_bitop3_b32 v0, v0, v1, 48 bitop3:0x6c
	v_lshrrev_b32_e32 v0, 1, v0
	v_mul_u32_u24_e32 v1, 0x1a00, v3
	v_or_b32_e32 v0, v1, v0
	v_ashrrev_i32_e32 v1, 31, v0
	v_lshl_add_u64 v[0:1], v[0:1], 1, s[4:5]
	v_lshlrev_b32_e32 v2, 3, v2
	s_mov_b64 s[10:11], 0x80
	v_ashrrev_i32_e32 v3, 31, v2
	v_lshl_add_u64 v[4:5], v[0:1], 0, s[10:11]
	v_readfirstlane_b32 s10, v6
	v_add_u32_e32 v7, 0x4000, v6
	s_mov_b32 m0, s10
	v_lshl_add_u64 v[2:3], v[2:3], 1, s[8:9]
	s_mov_b64 s[8:9], 0x4000
	global_load_lds_dwordx4 v[4:5], off
	v_lshl_add_u64 v[4:5], v[2:3], 0, s[8:9]
	v_readfirstlane_b32 s8, v7
	s_mov_b32 m0, s8
	s_mov_b64 s[8:9], 0x1a0080
	global_load_lds_dwordx4 v[4:5], off
	v_add_u32_e32 v4, 0x2000, v6
	v_lshl_add_u64 v[0:1], v[0:1], 0, s[8:9]
	v_readfirstlane_b32 s8, v4
	s_mov_b32 m0, s8
	s_mov_b64 s[8:9], 0x84000
	global_load_lds_dwordx4 v[0:1], off
	v_lshl_add_u64 v[0:1], v[2:3], 0, s[8:9]
	v_add_u32_e32 v2, 0x6000, v6
	s_nop 0
	v_readfirstlane_b32 s8, v2
	s_mov_b32 m0, s8
	v_readlane_b32 s8, v253, 60
	global_load_lds_dwordx4 v[0:1], off
	v_mov_b32_e32 v0, 0
	v_readlane_b32 s9, v253, 61
	v_mov_b32_e32 v1, v0
	v_mov_b32_e32 v2, v0
; #define WAIT_V(n) asm volatile("s_waitcnt vmcnt(" #n ")" ::: "memory")
; #define BAR __builtin_amdgcn_s_barrier()
; #define LDA_(dst, ai) _Pragma("unroll") for (int m = 0; m < 4; ++m) dst[m] = *(const bf16x8*)(sb + (ai) * 8192 + la0 + m * 1024)
; #define LDB_(dst) _Pragma("unroll") for (int bj = 0; bj < 2; ++bj) _Pragma("unroll") for (int n = 0; n < 2; ++n) dst[bj][n] = *(const bf16x8*)(sb + 16384 + bj * 8192 + lb0 + n * 1024)
; template <int MODE>
; DI void gemm_phase(const Params& p, int layer, int hf, unsigned char* shmc, int tid) {
;     ...
; #pragma unroll
;     for (int a = 0; a < 2; ++a)
; #pragma unroll
;       for (int b = 0; b < 2; ++b)
; #pragma unroll
;         for (int m = 0; m < 4; ++m)
; #pragma unroll
;           for (int n = 0; n < 2; ++n) acc[a][b][m][n] = (f32x4){0.f, 0.f, 0.f, 0.f};
;     const bf16_t* gA = (MODE == 0) ? A + (size_t)(brow >> 7) * nt * 4096 : A + (size_t)brow * lda; const bf16_t* gB = Bt + (size_t)(bcol >> 7) * nt * 4096;
;     ...
;     if (!pre) { STAGE_ALL(0, 0); STAGE_ALL(1, 1); }
;     STAGE_ALL(2, 2);
;     for (int kt = 0; kt < nt; ++kt) {
;       const int rem = nt - 1 - kt;
;       if (rem >= 2) WAIT_V(8); else if (rem == 1) WAIT_V(4); else WAIT_V(0);
;       BAR;
;       const unsigned char* sb = shmc + (kt & 3) * 32768;
;     ...
;       {
;         bf16x8 b0[2][2], a0[4], a1[4];
;         LDB_(b0); LDA_(a0, 0);
	v_mov_b32_e32 v3, v0
	v_mov_b32_e32 v4, v0
	v_mov_b32_e32 v5, v0
	v_mov_b32_e32 v6, v0
	v_mov_b32_e32 v7, v0
	v_mov_b32_e32 v8, v0
	v_mov_b32_e32 v9, v0
	v_mov_b32_e32 v10, v0
	v_mov_b32_e32 v11, v0
	v_mov_b32_e32 v12, v0
	v_mov_b32_e32 v13, v0
	v_mov_b32_e32 v14, v0
	v_mov_b32_e32 v15, v0
	v_mov_b32_e32 v64, v0
	v_mov_b32_e32 v65, v0
	v_mov_b32_e32 v66, v0
	v_mov_b32_e32 v67, v0
	v_mov_b32_e32 v68, v0
	v_mov_b32_e32 v69, v0
	v_mov_b32_e32 v70, v0
	v_mov_b32_e32 v71, v0
	v_mov_b32_e32 v72, v0
	v_mov_b32_e32 v73, v0
	v_mov_b32_e32 v74, v0
	v_mov_b32_e32 v75, v0
	v_mov_b32_e32 v76, v0
	v_mov_b32_e32 v77, v0
	v_mov_b32_e32 v78, v0
	v_mov_b32_e32 v79, v0
	v_mov_b32_e32 v80, v0
	v_mov_b32_e32 v81, v0
	v_mov_b32_e32 v82, v0
	v_mov_b32_e32 v83, v0
	v_mov_b32_e32 v84, v0
	v_mov_b32_e32 v85, v0
	v_mov_b32_e32 v86, v0
	v_mov_b32_e32 v87, v0
	v_mov_b32_e32 v92, v0
	v_mov_b32_e32 v93, v0
	v_mov_b32_e32 v94, v0
	v_mov_b32_e32 v95, v0
	v_mov_b32_e32 v100, v0
	v_mov_b32_e32 v101, v0
	v_mov_b32_e32 v102, v0
	v_mov_b32_e32 v103, v0
	v_mov_b32_e32 v88, v0
	v_mov_b32_e32 v89, v0
	v_mov_b32_e32 v90, v0
	v_mov_b32_e32 v91, v0
	v_mov_b32_e32 v96, v0
	v_mov_b32_e32 v97, v0
	v_mov_b32_e32 v98, v0
	v_mov_b32_e32 v99, v0
	v_mov_b32_e32 v104, v0
	v_mov_b32_e32 v105, v0
	v_mov_b32_e32 v106, v0
	v_mov_b32_e32 v107, v0
	v_mov_b32_e32 v108, v0
	v_mov_b32_e32 v109, v0
	v_mov_b32_e32 v110, v0
	v_mov_b32_e32 v111, v0
	v_mov_b32_e32 v112, v0
	v_mov_b32_e32 v113, v0
	v_mov_b32_e32 v114, v0
	v_mov_b32_e32 v115, v0
	v_mov_b32_e32 v116, v0
	v_mov_b32_e32 v117, v0
	v_mov_b32_e32 v118, v0
	v_mov_b32_e32 v119, v0
	v_mov_b32_e32 v120, v0
	v_mov_b32_e32 v121, v0
	v_mov_b32_e32 v122, v0
	v_mov_b32_e32 v123, v0
	v_mov_b32_e32 v124, v0
	v_mov_b32_e32 v125, v0
	v_mov_b32_e32 v126, v0
	v_mov_b32_e32 v127, v0
	v_mov_b32_e32 v16, v0
	v_mov_b32_e32 v17, v0
	v_mov_b32_e32 v18, v0
	v_mov_b32_e32 v19, v0
	v_mov_b32_e32 v20, v0
	v_mov_b32_e32 v21, v0
	v_mov_b32_e32 v22, v0
	v_mov_b32_e32 v23, v0
	v_mov_b32_e32 v24, v0
	v_mov_b32_e32 v25, v0
	v_mov_b32_e32 v26, v0
	v_mov_b32_e32 v27, v0
	v_mov_b32_e32 v28, v0
	v_mov_b32_e32 v29, v0
	v_mov_b32_e32 v30, v0
	v_mov_b32_e32 v31, v0
	v_mov_b32_e32 v32, v0
	v_mov_b32_e32 v33, v0
	v_mov_b32_e32 v34, v0
	v_mov_b32_e32 v35, v0
	v_mov_b32_e32 v36, v0
	v_mov_b32_e32 v37, v0
	v_mov_b32_e32 v38, v0
	v_mov_b32_e32 v39, v0
	v_mov_b32_e32 v40, v0
	v_mov_b32_e32 v41, v0
	v_mov_b32_e32 v42, v0
	v_mov_b32_e32 v43, v0
	v_mov_b32_e32 v44, v0
	v_mov_b32_e32 v45, v0
	v_mov_b32_e32 v46, v0
	v_mov_b32_e32 v47, v0
	v_mov_b32_e32 v48, v0
	v_mov_b32_e32 v49, v0
	v_mov_b32_e32 v50, v0
	v_mov_b32_e32 v51, v0
	v_mov_b32_e32 v52, v0
	v_mov_b32_e32 v53, v0
	v_mov_b32_e32 v54, v0
	v_mov_b32_e32 v55, v0
	v_mov_b32_e32 v56, v0
	v_mov_b32_e32 v57, v0
	v_mov_b32_e32 v58, v0
	v_mov_b32_e32 v59, v0
	v_mov_b32_e32 v60, v0
	v_mov_b32_e32 v61, v0
	v_mov_b32_e32 v62, v0
	v_mov_b32_e32 v63, v0
	v_lshlrev_b32_e32 v183, 4, v169
	v_and_b32_e32 v182, 32, v169
	v_bitop3_b32 v182, v183, v182, 48 bitop3:0x6c
	v_lshrrev_b32_e32 v184, 2, v169
	v_lshrrev_b32_e32 v182, 1, v182
	v_mul_u32_u24_e32 v184, 0x1a00, v184
	v_readfirstlane_b32 s29, v183
	v_add_u32_e32 v182, v182, v184
	v_lshlrev_b32_e32 v182, 1, v182
	v_add_u32_e32 v184, 32, v173
	v_add_u32_e32 v185, 0x10020, v173
	v_add3_u32 v186, v174, v172, 32
	s_add_u32 s98, s4, 0xc0
	s_addc_u32 s99, s5, 0
	s_add_u32 s100, s8, s6
	s_addc_u32 s101, s9, s7
	v_add_u32_e32 v187, 0x10000, v186
	s_add_i32 s29, s29, 32
	s_mov_b32 s28, 0
	s_waitcnt vmcnt(8)
	s_barrier
	ds_read_b128 v[140:143], v186 offset:16384
	ds_read_b128 v[144:147], v186 offset:17408
	ds_read_b128 v[132:135], v186 offset:24576
	ds_read_b128 v[128:131], v186 offset:25600
	ds_read_b128 v[136:139], v184
	ds_read_b128 v[148:151], v184 offset:1024
	ds_read_b128 v[152:155], v184 offset:2048
	ds_read_b128 v[178:181], v184 offset:3072
	.p2align 6
